# NSA pass 2: the four K-fragment LDS reads of each half issued together with counted waits (v[80:83] no longer reused per MFMA)
# baseline (speedup 1.0000x reference)
.LBB0_1576:
	v_add_u32_e32 v14, s0, v11
	v_add_u32_e32 v15, v14, v0
	ds_read_b128 v[80:83], v15
	ds_read_b128 v[84:87], v15 offset:32
	ds_read_b128 v[240:243], v15 offset:64
	ds_read_b128 v[244:247], v15 offset:96
	v_add_u32_e32 v14, 0xfffffe00, v13
	v_cmp_le_i32_e64 s[0:1], v14, v188
	s_waitcnt lgkmcnt(3)
	v_mfma_f32_32x32x16_bf16 v[64:79], v[80:83], v[144:147], v[48:63]
	s_waitcnt lgkmcnt(2)
	v_mfma_f32_32x32x16_bf16 v[64:79], v[84:87], v[148:151], v[64:79]
	s_waitcnt lgkmcnt(1)
	v_mfma_f32_32x32x16_bf16 v[64:79], v[240:243], v[152:155], v[64:79]
	s_waitcnt lgkmcnt(0)
	v_mfma_f32_32x32x16_bf16 v[64:79], v[244:247], v[156:159], v[64:79]
	s_nop 11
	v_exp_f32_e32 v64, v64
	v_exp_f32_e32 v65, v65
	v_exp_f32_e32 v66, v66
	v_exp_f32_e32 v67, v67
	v_mul_f32_e32 v64, v190, v64
	v_cndmask_b32_e64 v14, 0, v64, s[0:1]
	v_add_u32_e32 v64, 0xfffffe10, v13
	v_mul_f32_e32 v65, v190, v65
	v_cmp_le_i32_e64 s[0:1], v64, v188
	v_mul_f32_e32 v66, v190, v66
	v_mul_f32_e32 v67, v190, v67
	v_cndmask_b32_e64 v64, 0, v65, s[0:1]
	v_add_u32_e32 v65, 0xfffffe20, v13
	v_cmp_le_i32_e64 s[0:1], v65, v188
	v_add_f32_e32 v14, v14, v64
	s_nop 0
	v_cndmask_b32_e64 v65, 0, v66, s[0:1]
	v_add_u32_e32 v66, 0xfffffe30, v13
	v_cmp_le_i32_e64 s[0:1], v66, v188
	s_nop 1
	v_cndmask_b32_e64 v66, 0, v67, s[0:1]
	v_add_f32_e32 v64, v65, v66
	v_add_f32_e32 v14, v14, v64
	s_nop 0
	s_nop 1
	v_mov_b32_dpp v64, v14 quad_perm:[1,0,3,2] row_mask:0xf bank_mask:0xf
	v_add_f32_e32 v64, v14, v64
	s_nop 0
	s_nop 1
	v_mov_b32_dpp v65, v64 quad_perm:[2,3,0,1] row_mask:0xf bank_mask:0xf
	s_nop 0
	s_nop 1
	v_mov_b32_dpp v14, v66 quad_perm:[1,0,3,2] row_mask:0xf bank_mask:0xf
	v_add_f32_e32 v66, v66, v14
	s_nop 0
	s_nop 1
	v_mov_b32_dpp v67, v66 quad_perm:[2,3,0,1] row_mask:0xf bank_mask:0xf
	v_add_u32_e32 v14, s4, v191
	s_and_saveexec_b64 s[2:3], vcc
	s_cbranch_execz .LBB0_1581
	s_cmpk_gt_u32 s4, 0x7f
	s_cbranch_scc1 .LBB0_1579
	v_add_f32_e32 v64, v64, v65
	ds_add_f32 v12, v64

.LBB0_1596:
	s_or_b64 exec, exec, s[2:3]
	ds_read_b128 v[80:83], v15 offset:4608
	ds_read_b128 v[84:87], v15 offset:4640
	ds_read_b128 v[240:243], v15 offset:4672
	ds_read_b128 v[244:247], v15 offset:4704
	v_cmp_le_i32_e64 s[0:1], v13, v188
	s_waitcnt lgkmcnt(3)
	v_mfma_f32_32x32x16_bf16 v[64:79], v[80:83], v[144:147], v[48:63]
	s_waitcnt lgkmcnt(2)
	v_mfma_f32_32x32x16_bf16 v[64:79], v[84:87], v[148:151], v[64:79]
	s_waitcnt lgkmcnt(1)
	v_mfma_f32_32x32x16_bf16 v[64:79], v[240:243], v[152:155], v[64:79]
	s_waitcnt lgkmcnt(0)
	v_mfma_f32_32x32x16_bf16 v[64:79], v[244:247], v[156:159], v[64:79]
	s_nop 11
	v_exp_f32_e32 v15, v64
	v_exp_f32_e32 v65, v65
	v_exp_f32_e32 v66, v66
	v_add_u32_e32 v64, 16, v13
	v_mul_f32_e32 v15, v190, v15
	v_cndmask_b32_e64 v15, 0, v15, s[0:1]
	v_mul_f32_e32 v65, v190, v65
	v_cmp_le_i32_e64 s[0:1], v64, v188
	v_exp_f32_e32 v67, v67
	v_mul_f32_e32 v66, v190, v66
	v_cndmask_b32_e64 v64, 0, v65, s[0:1]
	v_add_u32_e32 v65, 32, v13
	v_cmp_le_i32_e64 s[0:1], v65, v188
	v_mul_f32_e32 v67, v190, v67
	v_add_f32_e32 v15, v15, v64
	v_cndmask_b32_e64 v65, 0, v66, s[0:1]
	v_add_u32_e32 v66, 48, v13
	v_cmp_le_i32_e64 s[0:1], v66, v188
	s_nop 1
	v_cndmask_b32_e64 v66, 0, v67, s[0:1]
	v_add_f32_e32 v64, v65, v66
	v_add_f32_e32 v15, v15, v64
	s_nop 1
	v_mov_b32_dpp v64, v15 quad_perm:[1,0,3,2] row_mask:0xf bank_mask:0xf
	v_add_f32_e32 v15, v15, v64
	s_nop 0
	s_nop 1
	v_mov_b32_dpp v65, v66 quad_perm:[1,0,3,2] row_mask:0xf bank_mask:0xf
	v_add_f32_e32 v65, v66, v65
	s_nop 1
	v_mov_b32_dpp v64, v15 quad_perm:[2,3,0,1] row_mask:0xf bank_mask:0xf
	s_nop 1
	v_mov_b32_dpp v66, v65 quad_perm:[2,3,0,1] row_mask:0xf bank_mask:0xf
	s_and_saveexec_b64 s[2:3], vcc
	s_cbranch_execz .LBB0_1601
	s_cmpk_gt_u32 s4, 0x7f
	s_cbranch_scc1 .LBB0_1599
	v_add_f32_e32 v15, v15, v64
	ds_add_f32 v12, v15 offset:32
